# S5 chunk loop: batch the 16 input-projection MFMAs ahead of their cvts (no per-MFMA nop stalls), hoist 33 loop-invariant LDS address adds, drop redundant A-operand zeroing, issue all 8 output-projecti
# speedup vs baseline: 1.0018x; 1.0018x over previous
; __device__ __forceinline__ unsigned cvt_pk_bf16(float lo, float hi) { f32x2_t v = {lo, hi}; bf16x2_t b = __builtin_convertvector(v, bf16x2_t); return __builtin_bit_cast(unsigned, b); }
; __device__ __forceinline__ void s5_phase(LAS unsigned char* lds, CParams* pp, int layer, int G, int c) {
;     ...
;         bf16x8 Cf[4];
; #pragma unroll
;         for (int kb = 0; kb < 4; ++kb) { const int pc = kb * 16 + lq * 4; const f32x4 cr = *(const f32x4*)(pp->in[9] + (pg * 16 + l15) * 64 + pc), ci = *(const f32x4*)(pp->in[10] + (pg * 16 + l15) * 64 + pc);
;             const unsigned w0 = cvt_pk_bf16(cr[0], -ci[0]), w1 = cvt_pk_bf16(cr[1], -ci[1]), w2 = cvt_pk_bf16(cr[2], -ci[2]), w3 = cvt_pk_bf16(cr[3], -ci[3]);
;             bf16x8 f; f[0] = (short)(w0 & 0xffff); f[1] = (short)(w0 >> 16); f[2] = (short)(w1 & 0xffff); f[3] = (short)(w1 >> 16); f[4] = (short)(w2 & 0xffff); f[5] = (short)(w2 >> 16); f[6] = (short)(w3 & 0xffff); f[7] = (short)(w3 >> 16);
;             Cf[kb] = f; }
;         const f32x4 dsk = *(const f32x4*)(pp->in[11] + layer * DM + g * 16 + 4 * lq);
;         float xr = 0.f, xi = 0.f;
;         const size_t colA = (size_t)g * 16 + (lq & 1) * 8, colO = (size_t)g * 16 + 4 * lq;
;     ...
;         bf16x8 Af_n[2]; u32x2 uo_n[2]; u32x2 yp_n[2];
; #pragma unroll
;         for (int tb = 0; tb < 2; ++tb) { const size_t t0 = S5_TOK(0, tb); Af_n[tb] = *(const bf16x8*)(U + t0 * DM + colA); uo_n[tb] = *(const u32x2*)(U + t0 * DM + colO); yp_n[tb] = (u32x2){0u, 0u}; }
.LBB0_361:
	s_or_b64 exec, exec, s[88:89]
	s_lshl_b64 s[60:61], s[64:65], 12
	v_lshl_or_b32 v28, v78, 2, s60
	v_mov_b32_e32 v29, s61
	v_lshl_add_u64 v[54:55], v[104:105], 0, v[28:29]
	v_lshl_add_u64 v[52:53], v[102:103], 0, v[28:29]
	global_load_dwordx4 v[28:31], v[54:55], off
	v_mul_f32_e32 v108, v27, v25
	s_waitcnt lgkmcnt(0)
	global_load_dwordx4 v[24:27], v[52:53], off
	s_ashr_i32 s60, s2, 5
	s_lshl_b32 s5, s4, 4
	s_ashr_i32 s61, s60, 31
	s_lshl_b32 s36, s4, 6
	v_or_b32_e32 v120, s5, v76
	v_mov_b32_e32 v122, 0
	v_mov_b32_e32 v109, v108
	v_xor_b32_e32 v106, 0x80000000, v107
	s_mov_b32 s67, 63
	v_mov_b32_e32 v118, 0
	v_mov_b32_e32 v119, 0
	v_mov_b32_e32 v116, 0
	v_mov_b32_e32 v117, 0
	v_mov_b32_e32 v123, v122
	s_waitcnt vmcnt(1)
	v_xor_b32_e32 v28, 0x80000000, v28
	s_waitcnt vmcnt(0)
	v_cvt_pk_bf16_f32 v28, v24, v28
	v_xor_b32_e32 v24, 0x80000000, v29
	v_cvt_pk_bf16_f32 v29, v25, v24
	v_xor_b32_e32 v24, 0x80000000, v30
	v_cvt_pk_bf16_f32 v30, v26, v24
	v_xor_b32_e32 v24, 0x80000000, v31
	v_cvt_pk_bf16_f32 v31, v27, v24
	global_load_dwordx4 v[24:27], v[52:53], off offset:64
	global_load_dwordx4 v[40:43], v[54:55], off offset:64
	s_waitcnt vmcnt(0)
	v_xor_b32_e32 v40, 0x80000000, v40
	v_cvt_pk_bf16_f32 v44, v24, v40
	v_xor_b32_e32 v24, 0x80000000, v41
	v_cvt_pk_bf16_f32 v45, v25, v24
	v_xor_b32_e32 v24, 0x80000000, v42
	v_cvt_pk_bf16_f32 v46, v26, v24
	v_xor_b32_e32 v24, 0x80000000, v43
	v_cvt_pk_bf16_f32 v47, v27, v24
	global_load_dwordx4 v[24:27], v[52:53], off offset:128
	global_load_dwordx4 v[40:43], v[54:55], off offset:128
	s_waitcnt vmcnt(0)
	v_xor_b32_e32 v40, 0x80000000, v40
	v_cvt_pk_bf16_f32 v48, v24, v40
	v_xor_b32_e32 v24, 0x80000000, v41
	v_cvt_pk_bf16_f32 v49, v25, v24
	v_xor_b32_e32 v24, 0x80000000, v42
	v_cvt_pk_bf16_f32 v50, v26, v24
	v_xor_b32_e32 v24, 0x80000000, v43
	v_cvt_pk_bf16_f32 v51, v27, v24
	global_load_dwordx4 v[24:27], v[52:53], off offset:192
	global_load_dwordx4 v[40:43], v[54:55], off offset:192
	v_or_b32_e32 v54, s5, v82
	s_lshl_b64 s[4:5], s[60:61], 11
	v_mov_b32_e32 v53, s5
	v_or_b32_e32 v52, s4, v84
	v_lshlrev_b64 v[52:53], 12, v[52:53]
	v_lshl_add_u64 v[52:53], s[80:81], 0, v[52:53]
	v_lshlrev_b32_e32 v178, 1, v54
	v_lshl_add_u64 v[54:55], v[52:53], 0, v[178:179]
	global_load_dwordx4 v[64:67], v[54:55], off
	v_lshlrev_b32_e32 v54, 1, v120
	v_mov_b32_e32 v55, v179
	s_mov_b64 s[60:61], 0x10000
	v_lshl_add_u64 v[56:57], v[52:53], 0, v[54:55]
	v_lshl_add_u64 v[52:53], v[52:53], 0, s[60:61]
	global_load_dwordx2 v[114:115], v[56:57], off
	v_lshl_add_u64 v[56:57], v[52:53], 0, v[178:179]
	v_lshl_add_u64 v[52:53], v[52:53], 0, v[54:55]
	global_load_dwordx4 v[60:63], v[56:57], off
	global_load_dwordx2 v[110:111], v[52:53], off
	v_mov_b32_e32 v53, s5
	v_or_b32_e32 v52, s4, v86
	v_lshl_add_u64 v[124:125], s[14:15], 0, v[54:55]
	v_lshlrev_b64 v[52:53], 12, v[52:53]
	v_lshl_add_u64 v[130:131], v[124:125], 0, v[52:53]
	v_mov_b32_e32 v113, s5
	v_or_b32_e32 v112, s4, v68
	v_lshl_add_u64 v[126:127], s[80:81], 0, v[178:179]
	v_lshl_add_u64 v[128:129], s[80:81], 0, v[54:55]
	v_lshl_add_u64 v[132:133], v[130:131], 0, s[60:61]
	v_lshl_add_u64 v[134:135], s[58:59], 0, v[54:55]
	s_waitcnt vmcnt(4)
	v_xor_b32_e32 v40, 0x80000000, v40
	v_cvt_pk_bf16_f32 v40, v24, v40
	v_xor_b32_e32 v24, 0x80000000, v41
	v_cvt_pk_bf16_f32 v41, v25, v24
	v_xor_b32_e32 v24, 0x80000000, v42
	v_cvt_pk_bf16_f32 v42, v26, v24
	v_xor_b32_e32 v24, 0x80000000, v43
	v_cvt_pk_bf16_f32 v43, v27, v24
	v_lshl_add_u64 v[24:25], v[80:81], 0, s[36:37]
	global_load_dwordx4 v[24:27], v[24:25], off
	v_add_u32_e32 v93, s10, v69
	v_add_u32_e32 v95, s11, v69
	v_add_u32_e32 v97, s22, v69
	v_add_u32_e32 v99, s23, v69
	v_add_u32_e32 v101, s35, v69
	v_add_u32_e32 v121, s54, v69
	v_add_u32_e32 v146, s91, v69
	v_add_u32_e32 v147, s92, v69
	v_add_u32_e32 v148, s93, v69
	v_add_u32_e32 v149, s94, v69
	v_add_u32_e32 v150, s95, v69
	v_add_u32_e32 v151, s96, v69
	v_add_u32_e32 v152, s97, v69
	v_add_u32_e32 v144, s55, v69
	v_add_u32_e32 v145, s90, v69
	v_add_u32_e32 v153, s6, v69
	v_add_u32_e32 v154, s38, v69
	v_add_u32_e32 v155, s39, v69
	v_add_u32_e32 v156, s19, v69
	v_add_u32_e32 v157, s72, v69
	v_add_u32_e32 v158, s73, v69
	v_add_u32_e32 v159, s16, v69
	v_add_u32_e32 v160, s17, v69
	v_add_u32_e32 v161, s30, v69
	v_add_u32_e32 v163, s31, v69
	v_add_u32_e32 v164, s26, v69
	v_add_u32_e32 v165, s27, v69
	v_add_u32_e32 v166, s70, v69
	v_add_u32_e32 v167, s71, v69
	v_add_u32_e32 v168, s52, v69
	v_add_u32_e32 v169, s53, v69
	v_add_u32_e32 v170, s50, v69
	v_add_u32_e32 v162, 0x1000, v89
	s_cmp_lg_u32 s67, 31
	s_cbranch_scc1 .LBB0_363

; #define LAS __attribute__((address_space(3)))
; __device__ __forceinline__ unsigned cvt_pk_bf16(float lo, float hi) { f32x2_t v = {lo, hi}; bf16x2_t b = __builtin_convertvector(v, bf16x2_t); return __builtin_bit_cast(unsigned, b); }
; __device__ __forceinline__ float bf_lo(unsigned u) { return __uint_as_float(u << 16); }
; __device__ __forceinline__ float bf_hi(unsigned u) { return __uint_as_float(u & 0xffff0000u); }
; __device__ __forceinline__ void s5_phase(LAS unsigned char* lds, CParams* pp, int layer, int G, int c) {
;     ...
;             bf16x8 Af[2];
; #pragma unroll
;             for (int tb = 0; tb < 2; ++tb) { Af[tb] = Af_n[tb]; if (lq >= 2) Af[tb] = (bf16x8){0, 0, 0, 0, 0, 0, 0, 0}; }
;             if (k + 1 < 64) {
; #pragma unroll
;                 for (int tb = 0; tb < 2; ++tb) Af_n[tb] = *(const bf16x8*)(U + S5_TOK(k + 1, tb) * DM + colA); }
; #pragma unroll
;             for (int tb = 0; tb < 2; ++tb)
; #pragma unroll
;                 for (int cb = 0; cb < 8; ++cb) { const f32x4 d = __builtin_amdgcn_mfma_f32_16x16x32_bf16(Bf[cb], Af[tb], (f32x4){0.f, 0.f, 0.f, 0.f}, 0, 0, 0);
;                     u32x2 w; w.x = cvt_pk_bf16(d[0], d[1]); w.y = cvt_pk_bf16(d[2], d[3]);
;                     *(LAS u32x2*)(xb + (tb * 16 + l15) * S5_PITCH + cb * 16 + 4 * lq) = w; }
;             asm volatile("s_waitcnt lgkmcnt(0)" ::: "memory");
;             { unsigned bw[32];
; #pragma unroll
;               for (int s = 0; s < 32; ++s) bw[s] = *(const LAS unsigned*)(xb + (dir ? 31 - s : s) * S5_PITCH + 2 * lane);
;               f32x2_t xv = {xr, xi}; const f32x2_t lrr = {lbr, lbr}, lii = {-lbi, lbi};
; #pragma unroll
;               for (int s = 0; s < 32; ++s) { const f32x2_t bv = {bf_lo(bw[s]), bf_hi(bw[s])};
;                   f32x2_t nv = lrr * xv + bv; nv = lii * xv.yx + nv; xv = nv; bw[s] = cvt_pk_bf16(xv.x, xv.y); }
.LBB0_363:
	s_waitcnt vmcnt(2)
	s_add_i32 s29, s28, 1
	s_add_i32 s66, s67, -1
	s_and_b64 s[4:5], s[78:79], exec
	s_cselect_b32 s36, s29, s66
	s_lshl_b64 s[4:5], s[36:37], 5
	v_mfma_f32_16x16x32_bf16 v[140:143], v[4:7], v[64:67], 0
	v_mfma_f32_16x16x32_bf16 v[210:213], v[0:3], v[64:67], 0
	v_mfma_f32_16x16x32_bf16 v[214:217], v[12:15], v[64:67], 0
	v_mfma_f32_16x16x32_bf16 v[218:221], v[8:11], v[64:67], 0
	v_mfma_f32_16x16x32_bf16 v[222:225], v[20:23], v[64:67], 0
	v_mfma_f32_16x16x32_bf16 v[226:229], v[16:19], v[64:67], 0
	v_mfma_f32_16x16x32_bf16 v[230:233], v[36:39], v[64:67], 0
	v_mfma_f32_16x16x32_bf16 v[234:237], v[32:35], v[64:67], 0
	v_lshl_add_u64 v[136:137], s[4:5], 0, v[112:113]
	v_lshlrev_b64 v[138:139], 12, v[136:137]
	v_lshl_add_u64 v[52:53], v[126:127], 0, v[138:139]
	global_load_dwordx4 v[56:59], v[52:53], off
	v_add_co_u32_e32 v52, vcc, s3, v52
	v_cvt_pk_bf16_f32 v140, v140, v141
	v_cvt_pk_bf16_f32 v141, v142, v143
	v_cvt_pk_bf16_f32 v210, v210, v211
	v_cvt_pk_bf16_f32 v211, v212, v213
	v_addc_co_u32_e32 v53, vcc, 0, v53, vcc
	ds_write2_b64 v89, v[140:141], v[210:211] offset1:4
	v_mfma_f32_16x16x32_bf16 v[140:143], v[4:7], v[60:63], 0
	v_mfma_f32_16x16x32_bf16 v[210:213], v[0:3], v[60:63], 0
	global_load_dwordx4 v[52:55], v[52:53], off
	v_cvt_pk_bf16_f32 v214, v214, v215
	v_cvt_pk_bf16_f32 v215, v216, v217
	v_cvt_pk_bf16_f32 v218, v218, v219
	v_cvt_pk_bf16_f32 v219, v220, v221
	ds_write2_b64 v89, v[214:215], v[218:219] offset0:8 offset1:12
	v_mfma_f32_16x16x32_bf16 v[214:217], v[12:15], v[60:63], 0
	v_mfma_f32_16x16x32_bf16 v[218:221], v[8:11], v[60:63], 0
	v_cvt_pk_bf16_f32 v222, v222, v223
	v_cvt_pk_bf16_f32 v223, v224, v225
	v_cvt_pk_bf16_f32 v226, v226, v227
	v_cvt_pk_bf16_f32 v227, v228, v229
	ds_write2_b64 v89, v[222:223], v[226:227] offset0:16 offset1:20
	v_mfma_f32_16x16x32_bf16 v[222:225], v[20:23], v[60:63], 0
	v_mfma_f32_16x16x32_bf16 v[226:229], v[16:19], v[60:63], 0
	v_cvt_pk_bf16_f32 v230, v230, v231
	v_cvt_pk_bf16_f32 v231, v232, v233
	v_cvt_pk_bf16_f32 v234, v234, v235
	v_cvt_pk_bf16_f32 v235, v236, v237
	ds_write2_b64 v89, v[230:231], v[234:235] offset0:24 offset1:28
	v_mfma_f32_16x16x32_bf16 v[230:233], v[36:39], v[60:63], 0
	v_mfma_f32_16x16x32_bf16 v[234:237], v[32:35], v[60:63], 0
	s_cmp_gt_u32 s28, 31
	s_cselect_b64 s[64:65], -1, 0
	s_mov_b64 s[4:5], -1
	s_and_b64 vcc, exec, s[64:65]
	v_cvt_pk_bf16_f32 v140, v140, v141
	v_cvt_pk_bf16_f32 v141, v142, v143
	v_cvt_pk_bf16_f32 v210, v210, v211
	v_cvt_pk_bf16_f32 v211, v212, v213
	ds_write2_b64 v162, v[140:141], v[210:211] offset0:32 offset1:36
	v_cvt_pk_bf16_f32 v214, v214, v215
	v_cvt_pk_bf16_f32 v215, v216, v217
	v_cvt_pk_bf16_f32 v218, v218, v219
	v_cvt_pk_bf16_f32 v219, v220, v221
	ds_write2_b64 v162, v[214:215], v[218:219] offset0:40 offset1:44
	v_cvt_pk_bf16_f32 v222, v222, v223
	v_cvt_pk_bf16_f32 v223, v224, v225
	v_cvt_pk_bf16_f32 v226, v226, v227
	v_cvt_pk_bf16_f32 v227, v228, v229
	ds_write2_b64 v162, v[222:223], v[226:227] offset0:48 offset1:52
	v_cvt_pk_bf16_f32 v230, v230, v231
	v_cvt_pk_bf16_f32 v231, v232, v233
	v_cvt_pk_bf16_f32 v234, v234, v235
	v_cvt_pk_bf16_f32 v235, v236, v237
	ds_write2_b64 v162, v[230:231], v[234:235] offset0:56 offset1:60
	s_waitcnt lgkmcnt(0)
	ds_read_b32 v61, v93
	ds_read_b32 v63, v95
	ds_read_b32 v64, v97
	ds_read_b32 v65, v99
	ds_read_b32 v66, v101
	ds_read_b32 v67, v121
	ds_read_b32 v140, v144
	ds_read_b32 v141, v145
	s_waitcnt lgkmcnt(7)
	v_lshlrev_b32_e32 v60, 16, v61
	v_and_b32_e32 v61, 0xffff0000, v61
	v_pk_fma_f32 v[60:61], v[108:109], v[122:123], v[60:61]
	s_waitcnt lgkmcnt(6)
	v_lshlrev_b32_e32 v62, 16, v63
	v_pk_fma_f32 v[60:61], v[106:107], v[122:123], v[60:61] op_sel:[0,1,0] op_sel_hi:[1,0,1]
	v_and_b32_e32 v63, 0xffff0000, v63
	v_pk_fma_f32 v[62:63], v[108:109], v[60:61], v[62:63]
	v_cvt_pk_bf16_f32 v196, v60, v61
	v_pk_fma_f32 v[60:61], v[106:107], v[60:61], v[62:63] op_sel:[0,1,0] op_sel_hi:[1,0,1]
	s_waitcnt lgkmcnt(5)
	v_lshlrev_b32_e32 v62, 16, v64
	v_and_b32_e32 v63, 0xffff0000, v64
	v_pk_fma_f32 v[62:63], v[108:109], v[60:61], v[62:63]
	v_cvt_pk_bf16_f32 v198, v60, v61
	v_pk_fma_f32 v[60:61], v[106:107], v[60:61], v[62:63] op_sel:[0,1,0] op_sel_hi:[1,0,1]
	s_waitcnt lgkmcnt(4)
	v_lshlrev_b32_e32 v62, 16, v65
	v_and_b32_e32 v63, 0xffff0000, v65
	v_pk_fma_f32 v[62:63], v[108:109], v[60:61], v[62:63]
	v_cvt_pk_bf16_f32 v64, v60, v61
	v_pk_fma_f32 v[60:61], v[106:107], v[60:61], v[62:63] op_sel:[0,1,0] op_sel_hi:[1,0,1]
	s_waitcnt lgkmcnt(3)
	v_lshlrev_b32_e32 v62, 16, v66
	v_and_b32_e32 v63, 0xffff0000, v66
	v_pk_fma_f32 v[62:63], v[108:109], v[60:61], v[62:63]
	v_cvt_pk_bf16_f32 v65, v60, v61
	v_pk_fma_f32 v[60:61], v[106:107], v[60:61], v[62:63] op_sel:[0,1,0] op_sel_hi:[1,0,1]
	s_waitcnt lgkmcnt(2)
	v_lshlrev_b32_e32 v62, 16, v67
	v_and_b32_e32 v63, 0xffff0000, v67
	ds_read_b32 v142, v146
	ds_read_b32 v143, v147
	ds_read_b32 v171, v148
	ds_read_b32 v172, v149
	ds_read_b32 v173, v150
	ds_read_b32 v174, v151
	ds_read_b32 v175, v152
	ds_read_b32 v178, v153
	v_pk_fma_f32 v[62:63], v[108:109], v[60:61], v[62:63]
	v_cvt_pk_bf16_f32 v66, v60, v61
	v_pk_fma_f32 v[60:61], v[106:107], v[60:61], v[62:63] op_sel:[0,1,0] op_sel_hi:[1,0,1]
	s_waitcnt lgkmcnt(9)
	v_lshlrev_b32_e32 v62, 16, v140
	v_and_b32_e32 v63, 0xffff0000, v140
	v_pk_fma_f32 v[62:63], v[108:109], v[60:61], v[62:63]
	v_cvt_pk_bf16_f32 v67, v60, v61
	v_pk_fma_f32 v[60:61], v[106:107], v[60:61], v[62:63] op_sel:[0,1,0] op_sel_hi:[1,0,1]
	s_waitcnt lgkmcnt(8)
	v_lshlrev_b32_e32 v62, 16, v141
	v_and_b32_e32 v63, 0xffff0000, v141
	v_pk_fma_f32 v[62:63], v[108:109], v[60:61], v[62:63]
	v_cvt_pk_bf16_f32 v140, v60, v61
	v_pk_fma_f32 v[60:61], v[106:107], v[60:61], v[62:63] op_sel:[0,1,0] op_sel_hi:[1,0,1]
	s_waitcnt lgkmcnt(7)
; #define LAS __attribute__((address_space(3)))
; __device__ __forceinline__ unsigned cvt_pk_bf16(float lo, float hi) { f32x2_t v = {lo, hi}; bf16x2_t b = __builtin_convertvector(v, bf16x2_t); return __builtin_bit_cast(unsigned, b); }
; __device__ __forceinline__ float bf_lo(unsigned u) { return __uint_as_float(u << 16); }
; __device__ __forceinline__ float bf_hi(unsigned u) { return __uint_as_float(u & 0xffff0000u); }
; __device__ __forceinline__ void s5_phase(LAS unsigned char* lds, CParams* pp, int layer, int G, int c) {
;     ...
;               for (int s = 0; s < 32; ++s) bw[s] = *(const LAS unsigned*)(xb + (dir ? 31 - s : s) * S5_PITCH + 2 * lane);
;               f32x2_t xv = {xr, xi}; const f32x2_t lrr = {lbr, lbr}, lii = {-lbi, lbi};
; #pragma unroll
;               for (int s = 0; s < 32; ++s) { const f32x2_t bv = {bf_lo(bw[s]), bf_hi(bw[s])};
;                   f32x2_t nv = lrr * xv + bv; nv = lii * xv.yx + nv; xv = nv; bw[s] = cvt_pk_bf16(xv.x, xv.y); }
	v_lshlrev_b32_e32 v62, 16, v142
	v_and_b32_e32 v63, 0xffff0000, v142
	v_pk_fma_f32 v[62:63], v[108:109], v[60:61], v[62:63]
	v_cvt_pk_bf16_f32 v141, v60, v61
	v_pk_fma_f32 v[60:61], v[106:107], v[60:61], v[62:63] op_sel:[0,1,0] op_sel_hi:[1,0,1]
	s_waitcnt lgkmcnt(6)
	v_lshlrev_b32_e32 v62, 16, v143
	v_and_b32_e32 v63, 0xffff0000, v143
	v_pk_fma_f32 v[62:63], v[108:109], v[60:61], v[62:63]
	v_cvt_pk_bf16_f32 v142, v60, v61
	v_pk_fma_f32 v[60:61], v[106:107], v[60:61], v[62:63] op_sel:[0,1,0] op_sel_hi:[1,0,1]
	s_waitcnt lgkmcnt(5)
	v_lshlrev_b32_e32 v62, 16, v171
	v_and_b32_e32 v63, 0xffff0000, v171
	v_pk_fma_f32 v[62:63], v[108:109], v[60:61], v[62:63]
	v_cvt_pk_bf16_f32 v143, v60, v61
	v_pk_fma_f32 v[60:61], v[106:107], v[60:61], v[62:63] op_sel:[0,1,0] op_sel_hi:[1,0,1]
	s_waitcnt lgkmcnt(4)
	v_lshlrev_b32_e32 v62, 16, v172
	v_and_b32_e32 v63, 0xffff0000, v172
	v_pk_fma_f32 v[62:63], v[108:109], v[60:61], v[62:63]
	v_cvt_pk_bf16_f32 v171, v60, v61
	v_pk_fma_f32 v[60:61], v[106:107], v[60:61], v[62:63] op_sel:[0,1,0] op_sel_hi:[1,0,1]
	s_waitcnt lgkmcnt(3)
	v_lshlrev_b32_e32 v62, 16, v173
	v_and_b32_e32 v63, 0xffff0000, v173
	v_pk_fma_f32 v[62:63], v[108:109], v[60:61], v[62:63]
	v_cvt_pk_bf16_f32 v172, v60, v61
	v_pk_fma_f32 v[60:61], v[106:107], v[60:61], v[62:63] op_sel:[0,1,0] op_sel_hi:[1,0,1]
	s_waitcnt lgkmcnt(2)
	v_lshlrev_b32_e32 v62, 16, v174
	v_and_b32_e32 v63, 0xffff0000, v174
	ds_read_b32 v180, v154
	ds_read_b32 v181, v155
	ds_read_b32 v182, v156
	ds_read_b32 v183, v157
	ds_read_b32 v184, v158
	ds_read_b32 v185, v159
	ds_read_b32 v186, v160
	ds_read_b32 v187, v161
	v_pk_fma_f32 v[62:63], v[108:109], v[60:61], v[62:63]
	v_cvt_pk_bf16_f32 v173, v60, v61
	v_pk_fma_f32 v[60:61], v[106:107], v[60:61], v[62:63] op_sel:[0,1,0] op_sel_hi:[1,0,1]
	s_waitcnt lgkmcnt(9)
	v_lshlrev_b32_e32 v62, 16, v175
	v_and_b32_e32 v63, 0xffff0000, v175
	v_pk_fma_f32 v[62:63], v[108:109], v[60:61], v[62:63]
	v_cvt_pk_bf16_f32 v174, v60, v61
	v_pk_fma_f32 v[60:61], v[106:107], v[60:61], v[62:63] op_sel:[0,1,0] op_sel_hi:[1,0,1]
	s_waitcnt lgkmcnt(8)
	v_lshlrev_b32_e32 v62, 16, v178
	v_and_b32_e32 v63, 0xffff0000, v178
	v_pk_fma_f32 v[62:63], v[108:109], v[60:61], v[62:63]
	v_cvt_pk_bf16_f32 v175, v60, v61
	v_pk_fma_f32 v[60:61], v[106:107], v[60:61], v[62:63] op_sel:[0,1,0] op_sel_hi:[1,0,1]
	s_waitcnt lgkmcnt(7)
	v_lshlrev_b32_e32 v62, 16, v180
	v_and_b32_e32 v63, 0xffff0000, v180
	v_pk_fma_f32 v[62:63], v[108:109], v[60:61], v[62:63]
	v_cvt_pk_bf16_f32 v178, v60, v61
	v_pk_fma_f32 v[60:61], v[106:107], v[60:61], v[62:63] op_sel:[0,1,0] op_sel_hi:[1,0,1]
	s_waitcnt lgkmcnt(6)
	v_lshlrev_b32_e32 v62, 16, v181
	v_and_b32_e32 v63, 0xffff0000, v181
	v_pk_fma_f32 v[62:63], v[108:109], v[60:61], v[62:63]
	v_cvt_pk_bf16_f32 v180, v60, v61
	v_pk_fma_f32 v[60:61], v[106:107], v[60:61], v[62:63] op_sel:[0,1,0] op_sel_hi:[1,0,1]
	s_waitcnt lgkmcnt(5)
	v_lshlrev_b32_e32 v62, 16, v182
	v_and_b32_e32 v63, 0xffff0000, v182
	v_pk_fma_f32 v[62:63], v[108:109], v[60:61], v[62:63]
	v_cvt_pk_bf16_f32 v181, v60, v61
	v_pk_fma_f32 v[60:61], v[106:107], v[60:61], v[62:63] op_sel:[0,1,0] op_sel_hi:[1,0,1]
	s_waitcnt lgkmcnt(4)
	v_lshlrev_b32_e32 v62, 16, v183
	v_and_b32_e32 v63, 0xffff0000, v183
	v_pk_fma_f32 v[62:63], v[108:109], v[60:61], v[62:63]
	v_cvt_pk_bf16_f32 v182, v60, v61
	v_pk_fma_f32 v[60:61], v[106:107], v[60:61], v[62:63] op_sel:[0,1,0] op_sel_hi:[1,0,1]
	s_waitcnt lgkmcnt(3)
	v_lshlrev_b32_e32 v62, 16, v184
	v_and_b32_e32 v63, 0xffff0000, v184
	v_pk_fma_f32 v[62:63], v[108:109], v[60:61], v[62:63]
	v_cvt_pk_bf16_f32 v183, v60, v61
	v_pk_fma_f32 v[60:61], v[106:107], v[60:61], v[62:63] op_sel:[0,1,0] op_sel_hi:[1,0,1]
	s_waitcnt lgkmcnt(2)
	v_lshlrev_b32_e32 v62, 16, v185
	v_and_b32_e32 v63, 0xffff0000, v185
	ds_read_b32 v188, v163
	ds_read_b32 v189, v164
	ds_read_b32 v190, v165
	ds_read_b32 v191, v166
	ds_read_b32 v192, v167
	ds_read_b32 v193, v168
	ds_read_b32 v194, v169
	ds_read_b32 v195, v170
	v_pk_fma_f32 v[62:63], v[108:109], v[60:61], v[62:63]
	v_cvt_pk_bf16_f32 v184, v60, v61
	v_pk_fma_f32 v[60:61], v[106:107], v[60:61], v[62:63] op_sel:[0,1,0] op_sel_hi:[1,0,1]
	s_waitcnt lgkmcnt(9)
	v_lshlrev_b32_e32 v62, 16, v186
	v_and_b32_e32 v63, 0xffff0000, v186
	v_pk_fma_f32 v[62:63], v[108:109], v[60:61], v[62:63]
	v_cvt_pk_bf16_f32 v185, v60, v61
	v_pk_fma_f32 v[60:61], v[106:107], v[60:61], v[62:63] op_sel:[0,1,0] op_sel_hi:[1,0,1]
	s_waitcnt lgkmcnt(8)
	v_lshlrev_b32_e32 v62, 16, v187
	v_and_b32_e32 v63, 0xffff0000, v187
	v_pk_fma_f32 v[62:63], v[108:109], v[60:61], v[62:63]
	v_cvt_pk_bf16_f32 v186, v60, v61
	v_pk_fma_f32 v[60:61], v[106:107], v[60:61], v[62:63] op_sel:[0,1,0] op_sel_hi:[1,0,1]
	s_waitcnt lgkmcnt(7)
	v_lshlrev_b32_e32 v62, 16, v188
	v_and_b32_e32 v63, 0xffff0000, v188
	v_pk_fma_f32 v[62:63], v[108:109], v[60:61], v[62:63]
	v_cvt_pk_bf16_f32 v187, v60, v61
	v_pk_fma_f32 v[60:61], v[106:107], v[60:61], v[62:63] op_sel:[0,1,0] op_sel_hi:[1,0,1]
	s_waitcnt lgkmcnt(6)
	v_lshlrev_b32_e32 v62, 16, v189
	v_and_b32_e32 v63, 0xffff0000, v189
	v_pk_fma_f32 v[62:63], v[108:109], v[60:61], v[62:63]
	v_cvt_pk_bf16_f32 v188, v60, v61
	v_pk_fma_f32 v[60:61], v[106:107], v[60:61], v[62:63] op_sel:[0,1,0] op_sel_hi:[1,0,1]
	s_waitcnt lgkmcnt(5)
	v_lshlrev_b32_e32 v62, 16, v190
	v_and_b32_e32 v63, 0xffff0000, v190
	v_pk_fma_f32 v[62:63], v[108:109], v[60:61], v[62:63]
	v_cvt_pk_bf16_f32 v189, v60, v61
	v_pk_fma_f32 v[60:61], v[106:107], v[60:61], v[62:63] op_sel:[0,1,0] op_sel_hi:[1,0,1]
	s_waitcnt lgkmcnt(4)
; #define LAS __attribute__((address_space(3)))
; __device__ __forceinline__ unsigned cvt_pk_bf16(float lo, float hi) { f32x2_t v = {lo, hi}; bf16x2_t b = __builtin_convertvector(v, bf16x2_t); return __builtin_bit_cast(unsigned, b); }
; __device__ __forceinline__ float bf_lo(unsigned u) { return __uint_as_float(u << 16); }
; __device__ __forceinline__ float bf_hi(unsigned u) { return __uint_as_float(u & 0xffff0000u); }
; __device__ __forceinline__ void s5_phase(LAS unsigned char* lds, CParams* pp, int layer, int G, int c) {
;     ...
;                   f32x2_t nv = lrr * xv + bv; nv = lii * xv.yx + nv; xv = nv; bw[s] = cvt_pk_bf16(xv.x, xv.y); }
;               xr = xv.x; xi = xv.y;
; #pragma unroll
;               for (int s = 0; s < 32; ++s) *(LAS unsigned*)(xb + (dir ? 31 - s : s) * S5_PITCH + 2 * lane) = bw[s]; }
;             asm volatile("s_waitcnt lgkmcnt(0)" ::: "memory");
;             f32x4 y[2];
; #pragma unroll
;             for (int tb = 0; tb < 2; ++tb) { y[tb] = (f32x4){0.f, 0.f, 0.f, 0.f};
; #pragma unroll
;                 for (int kb = 0; kb < 4; ++kb) { const bf16x8 xa = *(const LAS bf16x8*)(xb + (tb * 16 + l15) * S5_PITCH + kb * 32 + lq * 8); y[tb] = __builtin_amdgcn_mfma_f32_16x16x32_bf16(Cf[kb], xa, y[tb], 0, 0, 0); } }
;             asm volatile("s_waitcnt lgkmcnt(0)" ::: "memory");
; #pragma unroll
;             for (int tb = 0; tb < 2; ++tb) { const size_t tk = S5_TOK(k, tb);
;                 if (k < 32) {
;                     { u32x2 w; w.x = cvt_pk_bf16(y[tb][0], y[tb][1]); w.y = cvt_pk_bf16(y[tb][2], y[tb][3]); *(u32x2*)(YP + tk * DM + colO) = w; }
;                 } else {
;                     const float uu[4] = {bf_lo(uo_n[tb].x), bf_hi(uo_n[tb].x), bf_lo(uo_n[tb].y), bf_hi(uo_n[tb].y)}; float ge[4];
;                     const float ypv[4] = {bf_lo(yp_n[tb].x), bf_hi(yp_n[tb].x), bf_lo(yp_n[tb].y), bf_hi(yp_n[tb].y)};
; #pragma unroll
;                     for (int r = 0; r < 4; ++r) { const float tot = y[tb][r] + ypv[r] + dsk[r] * uu[r];
;                         const float zz = 0.7978845608f * (tot + 0.044715f * tot * tot * tot); ge[r] = tot * fast_sigmoid(2.0f * zz); }
;                     u32x2 w; w.x = cvt_pk_bf16(ge[0], ge[1]); w.y = cvt_pk_bf16(ge[2], ge[3]);
;                     *(u32x2*)(YS + tk * DM + colO) = w;
	v_lshlrev_b32_e32 v62, 16, v191
	v_and_b32_e32 v63, 0xffff0000, v191
	v_pk_fma_f32 v[62:63], v[108:109], v[60:61], v[62:63]
	v_cvt_pk_bf16_f32 v190, v60, v61
	v_pk_fma_f32 v[60:61], v[106:107], v[60:61], v[62:63] op_sel:[0,1,0] op_sel_hi:[1,0,1]
	s_waitcnt lgkmcnt(3)
	v_lshlrev_b32_e32 v62, 16, v192
	v_and_b32_e32 v63, 0xffff0000, v192
	v_pk_fma_f32 v[62:63], v[108:109], v[60:61], v[62:63]
	v_cvt_pk_bf16_f32 v191, v60, v61
	v_pk_fma_f32 v[60:61], v[106:107], v[60:61], v[62:63] op_sel:[0,1,0] op_sel_hi:[1,0,1]
	s_waitcnt lgkmcnt(2)
	v_lshlrev_b32_e32 v62, 16, v193
	v_and_b32_e32 v63, 0xffff0000, v193
	v_pk_fma_f32 v[62:63], v[108:109], v[60:61], v[62:63]
	v_cvt_pk_bf16_f32 v192, v60, v61
	v_pk_fma_f32 v[60:61], v[106:107], v[60:61], v[62:63] op_sel:[0,1,0] op_sel_hi:[1,0,1]
	s_waitcnt lgkmcnt(1)
	v_lshlrev_b32_e32 v62, 16, v194
	v_and_b32_e32 v63, 0xffff0000, v194
	v_pk_fma_f32 v[62:63], v[108:109], v[60:61], v[62:63]
	v_cvt_pk_bf16_f32 v193, v60, v61
	v_pk_fma_f32 v[60:61], v[106:107], v[60:61], v[62:63] op_sel:[0,1,0] op_sel_hi:[1,0,1]
	s_waitcnt lgkmcnt(0)
	v_lshlrev_b32_e32 v62, 16, v195
	v_and_b32_e32 v63, 0xffff0000, v195
	v_pk_fma_f32 v[62:63], v[108:109], v[60:61], v[62:63]
	v_cvt_pk_bf16_f32 v194, v60, v61
	v_pk_fma_f32 v[122:123], v[106:107], v[60:61], v[62:63] op_sel:[0,1,0] op_sel_hi:[1,0,1]
	s_nop 0
	v_cvt_pk_bf16_f32 v60, v122, v123
	ds_write_b32 v93, v196
	ds_write_b32 v95, v198
	ds_write_b32 v97, v64
	ds_write_b32 v99, v65
	ds_write_b32 v101, v66
	ds_write_b32 v121, v67
	ds_write_b32 v144, v140
	ds_write_b32 v145, v141
	ds_write_b32 v146, v142
	ds_write_b32 v147, v143
	ds_write_b32 v148, v171
	ds_write_b32 v149, v172
	ds_write_b32 v150, v173
	ds_write_b32 v151, v174
	ds_write_b32 v152, v175
	ds_write_b32 v153, v178
	ds_write_b32 v154, v180
	ds_write_b32 v155, v181
	ds_write_b32 v156, v182
	ds_write_b32 v157, v183
	ds_write_b32 v158, v184
	ds_write_b32 v159, v185
	ds_write_b32 v160, v186
	ds_write_b32 v161, v187
	ds_write_b32 v163, v188
	ds_write_b32 v164, v189
	ds_write_b32 v165, v190
	ds_write_b32 v166, v191
	ds_write_b32 v167, v192
	ds_write_b32 v168, v193
	ds_write_b32 v169, v194
	ds_write_b32 v170, v60
	s_waitcnt lgkmcnt(0)
	ds_read_b128 v[210:213], v91
	ds_read_b128 v[214:217], v91 offset:64
	ds_read_b128 v[218:221], v91 offset:128
	ds_read_b128 v[222:225], v91 offset:192
	ds_read_b128 v[226:229], v91 offset:4352
	ds_read_b128 v[230:233], v91 offset:4416
	ds_read_b128 v[234:237], v91 offset:4480
	ds_read_b128 v[140:143], v91 offset:4544
	s_waitcnt lgkmcnt(7)
	v_mfma_f32_16x16x32_bf16 v[64:67], v[28:31], v[210:213], 0
	s_waitcnt lgkmcnt(6)
	v_mfma_f32_16x16x32_bf16 v[64:67], v[44:47], v[214:217], v[64:67]
	s_waitcnt lgkmcnt(5)
	v_mfma_f32_16x16x32_bf16 v[64:67], v[48:51], v[218:221], v[64:67]
	s_waitcnt lgkmcnt(4)
	v_mfma_f32_16x16x32_bf16 v[64:67], v[40:43], v[222:225], v[64:67]
	s_waitcnt lgkmcnt(3)
	v_mfma_f32_16x16x32_bf16 v[60:63], v[28:31], v[226:229], 0
	s_waitcnt lgkmcnt(2)
	v_mfma_f32_16x16x32_bf16 v[60:63], v[44:47], v[230:233], v[60:63]
	s_waitcnt lgkmcnt(1)
	v_mfma_f32_16x16x32_bf16 v[60:63], v[48:51], v[234:237], v[60:63]
	s_waitcnt lgkmcnt(0)
	v_mfma_f32_16x16x32_bf16 v[60:63], v[40:43], v[140:143], v[60:63]
	s_nop 1
	s_cbranch_vccz .LBB0_365
	s_waitcnt vmcnt(2)
	v_lshlrev_b32_e32 v142, 16, v118
	v_and_b32_e32 v143, 0xffff0000, v118
	v_lshlrev_b32_e32 v140, 16, v114
	v_and_b32_e32 v141, 0xffff0000, v114
	v_pk_add_f32 v[142:143], v[64:65], v[142:143]
	v_and_b32_e32 v175, 0xffff0000, v119
	s_waitcnt vmcnt(2)
	v_pk_fma_f32 v[140:141], v[24:25], v[140:141], v[142:143]
	v_and_b32_e32 v174, 0xffff0000, v115
	v_mul_f32_e32 v142, 0x3d372713, v140
	v_mul_f32_e32 v143, 0x3d372713, v141
	v_mul_f32_e32 v142, v140, v142
	v_mul_f32_e32 v143, v141, v143
	v_fma_f32 v142, v140, v142, v140
	v_fma_f32 v143, v141, v143, v141
	v_mul_f32_e32 v142, 0x3f4c422a, v142
	v_mul_f32_e32 v143, 0x3f4c422a, v143
	v_add_f32_e32 v142, v142, v142
	v_add_f32_e32 v143, v143, v143
	v_mul_f32_e32 v142, 0xbfb8aa3b, v142
	v_mul_f32_e32 v143, 0xbfb8aa3b, v143
	v_exp_f32_e32 v142, v142
	v_exp_f32_e32 v143, v143
	v_lshlrev_b32_e32 v171, 16, v115
	v_lshlrev_b32_e32 v172, 16, v119
	v_add_f32_e32 v142, 1.0, v142
	v_add_f32_e32 v143, 1.0, v143
	v_rcp_f32_e32 v142, v142
	v_rcp_f32_e32 v143, v143
	v_pk_add_f32 v[180:181], v[66:67], v[174:175]
	v_mul_f32_e32 v173, v27, v174
	s_mov_b64 s[4:5], 0
	v_pk_mul_f32 v[140:141], v[140:141], v[142:143]
	v_add_f32_e32 v142, v66, v172
	v_mul_f32_e32 v172, v26, v171
	v_mov_b32_e32 v143, v181
	v_pk_add_f32 v[142:143], v[172:173], v[142:143]
	v_cvt_pk_bf16_f32 v140, v140, v141
	v_mul_f32_e32 v171, 0x3d372713, v142
	v_mul_f32_e32 v171, v142, v171
	v_fma_f32 v171, v142, v171, v142
	v_mul_f32_e32 v171, 0x3f4c422a, v171
	v_add_f32_e32 v171, v171, v171
	v_mul_f32_e32 v171, 0xbfb8aa3b, v171
	v_exp_f32_e32 v171, v171
	s_nop 0
	v_add_f32_e32 v171, 1.0, v171
	v_rcp_f32_e32 v172, v171
	v_mul_f32_e32 v171, 0x3d372713, v143
	v_mul_f32_e32 v171, v143, v171
	v_fma_f32 v171, v143, v171, v143
	v_mul_f32_e32 v171, 0x3f4c422a, v171
	v_add_f32_e32 v171, v171, v171
	v_mul_f32_e32 v171, 0xbfb8aa3b, v171
	v_exp_f32_e32 v171, v171
	s_nop 0
	v_add_f32_e32 v171, 1.0, v171
	v_rcp_f32_e32 v173, v171
	s_nop 0
	v_pk_mul_f32 v[142:143], v[142:143], v[172:173]

; __device__ __forceinline__ void norm_rows_final(float* x, const float* g, const float* rsq, int gw, int NGW, int lane) {
;     for (int m = gw; m < M_TOK; m += NGW) {
;         f32x4* xr = (f32x4*)(x + (size_t)m * DM) + lane; const float r = 1.0f / sqrtf(rsq[m] * (1.0f / DM) + EPS);
; #pragma unroll
;         for (int j = 0; j < 8; ++j) { const f32x4 gv = ((const f32x4*)g)[64 * j + lane]; xr[64 * j] = xr[64 * j] * r * gv; }
;     }
.LBB0_545:
	global_load_dword v24, v179, s[0:1]
	global_load_dwordx4 v[12:15], v[10:11], off offset:-4096
	global_load_dwordx4 v[16:19], v[0:1], off
	global_load_dwordx4 v[20:23], v[10:11], off offset:-3072
	s_add_i32 s34, s34, s18
	s_add_u32 s0, s0, s20
	s_addc_u32 s1, s1, s21
	s_cmpk_gt_i32 s34, 0x3fff
	s_waitcnt vmcnt(0)
	v_fmamk_f32 v24, v24, 0x3a000000, v201
	v_mul_f32_e32 v25, 0x4f800000, v24
	v_cmp_gt_f32_e32 vcc, s51, v24
	s_nop 1
	v_cndmask_b32_e32 v24, v24, v25, vcc
	v_sqrt_f32_e32 v25, v24
	s_nop 0
	v_add_u32_e32 v26, -1, v25
	v_add_u32_e32 v27, 1, v25
	v_fma_f32 v28, -v26, v25, v24
	v_fma_f32 v29, -v27, v25, v24
	v_cmp_ge_f32_e64 s[42:43], 0, v28
	s_nop 1
	v_cndmask_b32_e64 v25, v25, v26, s[42:43]
	v_cmp_lt_f32_e64 s[42:43], 0, v29
	s_nop 1
	v_cndmask_b32_e64 v25, v25, v27, s[42:43]
	v_mul_f32_e32 v26, 0x37800000, v25
	v_cndmask_b32_e32 v25, v25, v26, vcc
	v_cmp_class_f32_e32 vcc, v24, v202
	s_nop 1
	v_cndmask_b32_e32 v24, v25, v24, vcc
	v_div_scale_f32 v25, s[4:5], v24, v24, 1.0
	v_rcp_f32_e32 v27, v25
	v_div_scale_f32 v26, vcc, 1.0, v24, 1.0
	v_fma_f32 v28, -v25, v27, 1.0
	v_fmac_f32_e32 v27, v28, v27
	v_mul_f32_e32 v28, v26, v27
	v_fma_f32 v29, -v25, v28, v26
	v_fmac_f32_e32 v28, v29, v27
	v_fma_f32 v25, -v25, v28, v26
	v_div_fmas_f32 v25, v25, v27, v28
	v_div_fixup_f32 v24, v25, v24, 1.0
	v_pk_mul_f32 v[12:13], v[12:13], v[24:25] op_sel_hi:[1,0]
	v_pk_mul_f32 v[14:15], v[14:15], v[24:25] op_sel_hi:[1,0]
	v_pk_mul_f32 v[12:13], v[16:17], v[12:13]
	v_pk_mul_f32 v[14:15], v[18:19], v[14:15]
	global_store_dwordx4 v[10:11], v[12:15], off offset:-4096
	global_load_dwordx4 v[12:15], v[0:1], off offset:1024
	s_nop 0
	global_load_dwordx4 v[16:19], v[10:11], off offset:-2048
	v_pk_mul_f32 v[22:23], v[22:23], v[24:25] op_sel_hi:[1,0]
	v_pk_mul_f32 v[20:21], v[20:21], v[24:25] op_sel_hi:[1,0]
	s_waitcnt vmcnt(1)
	v_pk_mul_f32 v[14:15], v[14:15], v[22:23]
	v_pk_mul_f32 v[12:13], v[12:13], v[20:21]
	global_store_dwordx4 v[10:11], v[12:15], off offset:-3072
	global_load_dwordx4 v[12:15], v[0:1], off offset:2048
	s_nop 0
	global_load_dwordx4 v[20:23], v[10:11], off offset:-1024
	s_waitcnt vmcnt(3)
	v_pk_mul_f32 v[18:19], v[24:25], v[18:19] op_sel_hi:[0,1]
	v_pk_mul_f32 v[16:17], v[24:25], v[16:17] op_sel_hi:[0,1]
	s_waitcnt vmcnt(1)
	v_pk_mul_f32 v[12:13], v[12:13], v[16:17]
	v_pk_mul_f32 v[14:15], v[14:15], v[18:19]
	global_store_dwordx4 v[10:11], v[12:15], off offset:-2048
	global_load_dwordx4 v[12:15], v[0:1], off offset:3072
	s_nop 0
	global_load_dwordx4 v[16:19], v[10:11], off
	s_waitcnt vmcnt(3)
	v_pk_mul_f32 v[22:23], v[24:25], v[22:23] op_sel_hi:[0,1]
	v_pk_mul_f32 v[20:21], v[24:25], v[20:21] op_sel_hi:[0,1]
	s_waitcnt vmcnt(1)
	v_pk_mul_f32 v[12:13], v[12:13], v[20:21]
	v_pk_mul_f32 v[14:15], v[14:15], v[22:23]
	global_store_dwordx4 v[10:11], v[12:15], off offset:-1024
	global_load_dwordx4 v[12:15], v[2:3], off
	s_nop 0
	global_load_dwordx4 v[20:23], v[10:11], off offset:1024
	s_waitcnt vmcnt(3)
	v_pk_mul_f32 v[18:19], v[24:25], v[18:19] op_sel_hi:[0,1]
	v_pk_mul_f32 v[16:17], v[24:25], v[16:17] op_sel_hi:[0,1]
	s_waitcnt vmcnt(1)
	v_pk_mul_f32 v[12:13], v[12:13], v[16:17]
	v_pk_mul_f32 v[14:15], v[14:15], v[18:19]
	global_store_dwordx4 v[10:11], v[12:15], off
	global_load_dwordx4 v[12:15], v[4:5], off
	s_nop 0
	global_load_dwordx4 v[16:19], v[10:11], off offset:2048
	s_waitcnt vmcnt(3)
	v_pk_mul_f32 v[22:23], v[24:25], v[22:23] op_sel_hi:[0,1]
	v_pk_mul_f32 v[20:21], v[24:25], v[20:21] op_sel_hi:[0,1]
	s_waitcnt vmcnt(1)
	v_pk_mul_f32 v[12:13], v[12:13], v[20:21]
	v_pk_mul_f32 v[14:15], v[14:15], v[22:23]
	global_store_dwordx4 v[10:11], v[12:15], off offset:1024
	global_load_dwordx4 v[12:15], v[6:7], off
	s_nop 0
	global_load_dwordx4 v[20:23], v[10:11], off offset:3072
	s_waitcnt vmcnt(3)
	v_pk_mul_f32 v[18:19], v[24:25], v[18:19] op_sel_hi:[0,1]
	v_pk_mul_f32 v[16:17], v[24:25], v[16:17] op_sel_hi:[0,1]
	s_waitcnt vmcnt(1)
	v_pk_mul_f32 v[12:13], v[12:13], v[16:17]
	v_pk_mul_f32 v[14:15], v[14:15], v[18:19]
	global_store_dwordx4 v[10:11], v[12:15], off offset:2048
	global_load_dwordx4 v[12:15], v[8:9], off
	s_waitcnt vmcnt(2)
	v_pk_mul_f32 v[16:17], v[24:25], v[22:23] op_sel_hi:[0,1]
	v_pk_mul_f32 v[18:19], v[24:25], v[20:21] op_sel_hi:[0,1]
	s_waitcnt vmcnt(0)
	v_pk_mul_f32 v[12:13], v[12:13], v[18:19]
	v_pk_mul_f32 v[14:15], v[14:15], v[16:17]
	global_store_dwordx4 v[10:11], v[12:15], off offset:3072
	v_lshl_add_u64 v[10:11], v[10:11], 0, s[68:69]
	s_cbranch_scc0 .LBB0_545
	s_branch .LBB0_12
